# inter-phase barriers 2..8 replaced by a lean hand-written barrier: per-XCD arrival counter, one add per XCD to the top counter, every workgroup polls the monotonic top counter directly (no TOPGEN / XG
# speedup vs baseline: 1.0057x; 1.0057x over previous
; __device__ __forceinline__ unsigned xb_ld(unsigned* p)              { return __hip_atomic_load(p, __ATOMIC_RELAXED, __HIP_MEMORY_SCOPE_AGENT); }
; __device__ __forceinline__ unsigned xb_add(unsigned* p, unsigned v) { return __hip_atomic_fetch_add(p, v, __ATOMIC_RELAXED, __HIP_MEMORY_SCOPE_AGENT); }
; #define XB_SPIN(cond, bar) do { unsigned _sp = 0; while (cond) { __builtin_amdgcn_s_sleep(1); \
;     if ((++_sp & 255u) == 0u) { if (xb_ld(&(bar)[XB_TMO])) break; if (_sp > XB_SPIN_CAP) { atomicAdd(&(bar)[XB_TMO], 1u); break; } } } } while (0)
; __device__ __forceinline__ void xcd_barrier(const XcdBarrier& b) {
;     asm volatile("s_waitcnt vmcnt(0)" ::: "memory");
;     __syncthreads();
;     if (threadIdx.x == 0) {
;         unsigned* bar = b.bar;
;         __builtin_amdgcn_s_waitcnt(0);
;         unsigned nloc = b.st[0], nx = b.st[1];
;         if (nloc == 0u) { xcd_barrier_complete(bar, b.x, nloc, nx); b.st[0] = nloc; b.st[1] = nx; }
;         const unsigned old = xb_add(&bar[XB_XSUB(b.x)], 1u);
;         const unsigned gen = old / nloc;
;         if (old + 1u == (gen + 1u) * nloc) {
;             __builtin_amdgcn_fence(__ATOMIC_RELEASE, "agent");
;             asm volatile("s_waitcnt vmcnt(0)" ::: "memory");
;             const unsigned og = xb_add(&bar[XB_TOP], 1u);
;             const unsigned tg = og / nx;
;             if (og + 1u == (tg + 1u) * nx) xb_add(&bar[XB_TOPGEN], 1u);
;             else XB_SPIN(xb_ld(&bar[XB_TOPGEN]) == tg, bar);
;             __builtin_amdgcn_fence(__ATOMIC_ACQUIRE, "agent");
;             xb_add(&bar[XB_XGEN(b.x)], 1u);
;             asm volatile("s_waitcnt vmcnt(0)" ::: "memory");
;         } else {
;             XB_SPIN(xb_ld(&bar[XB_XGEN(b.x)]) == gen, bar);
;             __builtin_amdgcn_fence(__ATOMIC_ACQUIRE, "agent");
;             asm volatile("s_waitcnt vmcnt(0)" ::: "memory");
;         }
.LBB0_153:
	s_waitcnt vmcnt(0)
	s_waitcnt lgkmcnt(0)
	s_barrier
	s_mov_b64 s[4:5], exec
	v_readlane_b32 s0, v244, 4
	v_readlane_b32 s1, v244, 5
	s_and_b64 s[0:1], s[4:5], s[0:1]
	s_mov_b64 exec, s[0:1]
	s_cbranch_execz .Lxb1_done
	v_mov_b32_e32 v0, 0x22400
	ds_read2_b32 v[0:1], v0 offset1:1
	s_getreg_b32 s6, hwreg(HW_REG_XCC_ID, 0, 4)
	s_and_b32 s6, s6, 15
	s_lshl_b32 s6, s6, 8
	s_addk_i32 s6, 0x1400
	v_mov_b32_e32 v2, s6
	v_mov_b32_e32 v3, 1
	global_atomic_add v2, v2, v3, s[40:41] sc0
	s_waitcnt vmcnt(0) lgkmcnt(0)
	v_readfirstlane_b32 s7, v2
	v_readfirstlane_b32 s8, v0
	v_readfirstlane_b32 s9, v1
	s_mul_i32 s10, s8, 2
	s_add_i32 s7, s7, 1
	s_cmp_lg_u32 s7, s10
	s_cbranch_scc1 .Lxb1_poll
	buffer_wbl2 sc1
	s_waitcnt vmcnt(0)
	v_mov_b32_e32 v2, 0x3400
	global_atomic_add v2, v3, s[40:41]
.Lxb1_poll:
	s_mul_i32 s10, s9, 2
	v_mov_b32_e32 v2, 0x3400
	s_mov_b32 s11, 0
.Lxb1_spin:
	global_load_dword v4, v2, s[40:41] sc1
	s_waitcnt vmcnt(0)
	v_readfirstlane_b32 s7, v4
	s_cmp_ge_u32 s7, s10
	s_cbranch_scc1 .Lxb1_rel
	s_sleep 1
	s_add_i32 s11, s11, 1
	s_cmp_lt_u32 s11, 0x20000
	s_cbranch_scc1 .Lxb1_spin
.Lxb1_rel:
	buffer_inv sc1
	s_waitcnt vmcnt(0)
.Lxb1_done:
	s_or_b64 exec, exec, s[4:5]
	s_branch .Lxb1_after

; #define PHASE_IDS() int tid_p = threadIdx.x; asm volatile("" : "+v"(tid_p)); const int lane = tid_p & 63; const int wave_p = __builtin_amdgcn_readfirstlane(tid_p >> 6); \
;     const int gw = vcu * NWAVES + wave_p, NGW = G * NWAVES; const size_t gt = (size_t)bx * NTHREADS + tid_p, NGT = (size_t)G * NTHREADS; (void)lane; (void)gw; (void)NGW; (void)gt; (void)NGT
; __global__ void __launch_bounds__(NTHREADS, 2) fwd_megakernel(Args args) {
;     ...
;     {
;         PHASE_IDS();
;         constexpr int TB = 32;
;         const size_t nitems = (size_t)(MTOK / TB) * 128;
;         for (size_t it = gt; it < nitems; it += NGT) {
;             const size_t tok0 = (it >> 7) * TB; const int ac = (int)(it & 127), h = ac >> 4, c0 = ac * 8;
; #pragma unroll 4
;             for (int t = 0; t < TB; ++t) {
.Lxb1_after:
	v_mov_b32_e32 v2, v178
	v_readlane_b32 s0, v244, 2
	s_waitcnt lgkmcnt(0)
	s_barrier
	v_readlane_b32 s1, v244, 3
	v_ashrrev_i32_e32 v3, 31, v2
	s_nop 0
	v_lshl_add_u64 v[0:1], s[0:1], 0, v[2:3]
	s_mov_b64 s[0:1], 0x20000
	v_cmp_gt_u64_e32 vcc, s[0:1], v[0:1]
	s_and_saveexec_b64 s[6:7], vcc
	s_cbranch_execz .LBB0_211
	v_and_b32_e32 v6, 0x70, v2
	v_and_b32_e32 v4, 0x7f, v2
	v_mov_b32_e32 v5, 0
	v_lshlrev_b32_e32 v4, 4, v4
	v_lshrrev_b32_e32 v6, 2, v6
	v_mov_b32_e32 v7, v5
	s_mov_b64 s[8:9], 0
	s_mov_b32 s0, 0x7fe0000
	s_mov_b32 s1, 0x3ff0000
	s_mov_b32 s29, 0xffc00
	s_mov_b32 s33, 0x7c00000
	s_mov_b32 s46, 0xbc00000
	s_brev_b32 s47, 16
	s_movk_i32 s62, 0x1000
	s_mov_b32 s63, 0x7c01000
	s_mov_b32 s64, 0xbc01000
	s_mov_b32 s65, 0x8001000
	s_movk_i32 s66, 0x2000
	s_mov_b64 s[10:11], 0x4000
	s_mov_b64 s[56:57], 0x2000
	s_mov_b64 s[58:59], 0x80
	s_mov_b64 s[60:61], 0x1ffff
	v_mov_b64_e32 v[8:9], v[0:1]

; __device__ __forceinline__ unsigned xb_ld(unsigned* p)              { return __hip_atomic_load(p, __ATOMIC_RELAXED, __HIP_MEMORY_SCOPE_AGENT); }
; __device__ __forceinline__ unsigned xb_add(unsigned* p, unsigned v) { return __hip_atomic_fetch_add(p, v, __ATOMIC_RELAXED, __HIP_MEMORY_SCOPE_AGENT); }
; #define XB_SPIN(cond, bar) do { unsigned _sp = 0; while (cond) { __builtin_amdgcn_s_sleep(1); \
;     if ((++_sp & 255u) == 0u) { if (xb_ld(&(bar)[XB_TMO])) break; if (_sp > XB_SPIN_CAP) { atomicAdd(&(bar)[XB_TMO], 1u); break; } } } } while (0)
; __device__ __forceinline__ void xcd_barrier(const XcdBarrier& b) {
;     asm volatile("s_waitcnt vmcnt(0)" ::: "memory");
;     __syncthreads();
;     if (threadIdx.x == 0) {
;         unsigned* bar = b.bar;
;         __builtin_amdgcn_s_waitcnt(0);
;         unsigned nloc = b.st[0], nx = b.st[1];
;         if (nloc == 0u) { xcd_barrier_complete(bar, b.x, nloc, nx); b.st[0] = nloc; b.st[1] = nx; }
;         const unsigned old = xb_add(&bar[XB_XSUB(b.x)], 1u);
;         const unsigned gen = old / nloc;
;         if (old + 1u == (gen + 1u) * nloc) {
;             __builtin_amdgcn_fence(__ATOMIC_RELEASE, "agent");
;             asm volatile("s_waitcnt vmcnt(0)" ::: "memory");
;             const unsigned og = xb_add(&bar[XB_TOP], 1u);
;             const unsigned tg = og / nx;
;             if (og + 1u == (tg + 1u) * nx) xb_add(&bar[XB_TOPGEN], 1u);
;             else XB_SPIN(xb_ld(&bar[XB_TOPGEN]) == tg, bar);
;             __builtin_amdgcn_fence(__ATOMIC_ACQUIRE, "agent");
;             xb_add(&bar[XB_XGEN(b.x)], 1u);
;             asm volatile("s_waitcnt vmcnt(0)" ::: "memory");
;         } else {
;             XB_SPIN(xb_ld(&bar[XB_XGEN(b.x)]) == gen, bar);
;             __builtin_amdgcn_fence(__ATOMIC_ACQUIRE, "agent");
;             asm volatile("s_waitcnt vmcnt(0)" ::: "memory");
;         }
.LBB0_216:
	s_or_b64 exec, exec, s[4:5]
	s_waitcnt vmcnt(0)
	s_barrier
	s_mov_b64 s[4:5], exec
	v_readlane_b32 s0, v244, 4
	v_readlane_b32 s1, v244, 5
	s_and_b64 s[0:1], s[4:5], s[0:1]
	s_mov_b64 exec, s[0:1]
	s_cbranch_execz .Lxb2_done
	v_mov_b32_e32 v0, 0x22400
	ds_read2_b32 v[0:1], v0 offset1:1
	s_getreg_b32 s6, hwreg(HW_REG_XCC_ID, 0, 4)
	s_and_b32 s6, s6, 15
	s_lshl_b32 s6, s6, 8
	s_addk_i32 s6, 0x1400
	v_mov_b32_e32 v2, s6
	v_mov_b32_e32 v3, 1
	global_atomic_add v2, v2, v3, s[40:41] sc0
	s_waitcnt vmcnt(0) lgkmcnt(0)
	v_readfirstlane_b32 s7, v2
	v_readfirstlane_b32 s8, v0
	v_readfirstlane_b32 s9, v1
	s_mul_i32 s10, s8, 3
	s_add_i32 s7, s7, 1
	s_cmp_lg_u32 s7, s10
	s_cbranch_scc1 .Lxb2_poll
	buffer_wbl2 sc1
	s_waitcnt vmcnt(0)
	v_mov_b32_e32 v2, 0x3400
	global_atomic_add v2, v3, s[40:41]
.Lxb2_poll:
	s_mul_i32 s10, s9, 3
	v_mov_b32_e32 v2, 0x3400
	s_mov_b32 s11, 0

; __device__ __forceinline__ unsigned xb_ld(unsigned* p)              { return __hip_atomic_load(p, __ATOMIC_RELAXED, __HIP_MEMORY_SCOPE_AGENT); }
; __device__ __forceinline__ unsigned xb_add(unsigned* p, unsigned v) { return __hip_atomic_fetch_add(p, v, __ATOMIC_RELAXED, __HIP_MEMORY_SCOPE_AGENT); }
; #define XB_SPIN(cond, bar) do { unsigned _sp = 0; while (cond) { __builtin_amdgcn_s_sleep(1); \
;     if ((++_sp & 255u) == 0u) { if (xb_ld(&(bar)[XB_TMO])) break; if (_sp > XB_SPIN_CAP) { atomicAdd(&(bar)[XB_TMO], 1u); break; } } } } while (0)
; __device__ __forceinline__ void xcd_barrier(const XcdBarrier& b) {
;     asm volatile("s_waitcnt vmcnt(0)" ::: "memory");
;     __syncthreads();
;     if (threadIdx.x == 0) {
;         unsigned* bar = b.bar;
;         __builtin_amdgcn_s_waitcnt(0);
;         unsigned nloc = b.st[0], nx = b.st[1];
;         if (nloc == 0u) { xcd_barrier_complete(bar, b.x, nloc, nx); b.st[0] = nloc; b.st[1] = nx; }
;         const unsigned old = xb_add(&bar[XB_XSUB(b.x)], 1u);
;         const unsigned gen = old / nloc;
;         if (old + 1u == (gen + 1u) * nloc) {
;             __builtin_amdgcn_fence(__ATOMIC_RELEASE, "agent");
;             asm volatile("s_waitcnt vmcnt(0)" ::: "memory");
;             const unsigned og = xb_add(&bar[XB_TOP], 1u);
;             const unsigned tg = og / nx;
;             if (og + 1u == (tg + 1u) * nx) xb_add(&bar[XB_TOPGEN], 1u);
;             else XB_SPIN(xb_ld(&bar[XB_TOPGEN]) == tg, bar);
;             __builtin_amdgcn_fence(__ATOMIC_ACQUIRE, "agent");
;             xb_add(&bar[XB_XGEN(b.x)], 1u);
;             asm volatile("s_waitcnt vmcnt(0)" ::: "memory");
;         } else {
;             XB_SPIN(xb_ld(&bar[XB_XGEN(b.x)]) == gen, bar);
;             __builtin_amdgcn_fence(__ATOMIC_ACQUIRE, "agent");
;             asm volatile("s_waitcnt vmcnt(0)" ::: "memory");
;         }
.LBB0_288:
	s_waitcnt vmcnt(0)
	s_waitcnt vmcnt(0)
	s_barrier
	s_mov_b64 s[4:5], exec
	v_readlane_b32 s0, v244, 4
	v_readlane_b32 s1, v244, 5
	s_and_b64 s[0:1], s[4:5], s[0:1]
	s_mov_b64 exec, s[0:1]
	s_cbranch_execz .Lxb3_done
	v_mov_b32_e32 v0, 0x22400
	ds_read2_b32 v[0:1], v0 offset1:1
	s_getreg_b32 s6, hwreg(HW_REG_XCC_ID, 0, 4)
	s_and_b32 s6, s6, 15
	s_lshl_b32 s6, s6, 8
	s_addk_i32 s6, 0x1400
	v_mov_b32_e32 v2, s6
	v_mov_b32_e32 v3, 1
	global_atomic_add v2, v2, v3, s[40:41] sc0
	s_waitcnt vmcnt(0) lgkmcnt(0)
	v_readfirstlane_b32 s7, v2
	v_readfirstlane_b32 s8, v0
	v_readfirstlane_b32 s9, v1
	s_mul_i32 s10, s8, 4
	s_add_i32 s7, s7, 1
	s_cmp_lg_u32 s7, s10
	s_cbranch_scc1 .Lxb3_poll
	buffer_wbl2 sc1
	s_waitcnt vmcnt(0)
	v_mov_b32_e32 v2, 0x3400
	global_atomic_add v2, v3, s[40:41]
.Lxb3_poll:
	s_mul_i32 s10, s9, 4
	v_mov_b32_e32 v2, 0x3400
	s_mov_b32 s11, 0

; __device__ __forceinline__ unsigned xb_ld(unsigned* p)              { return __hip_atomic_load(p, __ATOMIC_RELAXED, __HIP_MEMORY_SCOPE_AGENT); }
; __device__ __forceinline__ unsigned xb_add(unsigned* p, unsigned v) { return __hip_atomic_fetch_add(p, v, __ATOMIC_RELAXED, __HIP_MEMORY_SCOPE_AGENT); }
; #define XB_SPIN(cond, bar) do { unsigned _sp = 0; while (cond) { __builtin_amdgcn_s_sleep(1); \
;     if ((++_sp & 255u) == 0u) { if (xb_ld(&(bar)[XB_TMO])) break; if (_sp > XB_SPIN_CAP) { atomicAdd(&(bar)[XB_TMO], 1u); break; } } } } while (0)
; __device__ __forceinline__ void xcd_barrier(const XcdBarrier& b) {
;     asm volatile("s_waitcnt vmcnt(0)" ::: "memory");
;     __syncthreads();
;     if (threadIdx.x == 0) {
;         unsigned* bar = b.bar;
;         __builtin_amdgcn_s_waitcnt(0);
;         unsigned nloc = b.st[0], nx = b.st[1];
;         if (nloc == 0u) { xcd_barrier_complete(bar, b.x, nloc, nx); b.st[0] = nloc; b.st[1] = nx; }
;         const unsigned old = xb_add(&bar[XB_XSUB(b.x)], 1u);
;         const unsigned gen = old / nloc;
;         if (old + 1u == (gen + 1u) * nloc) {
;             __builtin_amdgcn_fence(__ATOMIC_RELEASE, "agent");
;             asm volatile("s_waitcnt vmcnt(0)" ::: "memory");
;             const unsigned og = xb_add(&bar[XB_TOP], 1u);
;             const unsigned tg = og / nx;
;             if (og + 1u == (tg + 1u) * nx) xb_add(&bar[XB_TOPGEN], 1u);
;             else XB_SPIN(xb_ld(&bar[XB_TOPGEN]) == tg, bar);
;             __builtin_amdgcn_fence(__ATOMIC_ACQUIRE, "agent");
;             xb_add(&bar[XB_XGEN(b.x)], 1u);
;             asm volatile("s_waitcnt vmcnt(0)" ::: "memory");
;         } else {
;             XB_SPIN(xb_ld(&bar[XB_XGEN(b.x)]) == gen, bar);
;             __builtin_amdgcn_fence(__ATOMIC_ACQUIRE, "agent");
;             asm volatile("s_waitcnt vmcnt(0)" ::: "memory");
;         }
.LBB0_343:
	s_waitcnt vmcnt(0)
	s_barrier
	s_mov_b64 s[4:5], exec
	v_readlane_b32 s0, v244, 4
	v_readlane_b32 s1, v244, 5
	s_and_b64 s[0:1], s[4:5], s[0:1]
	s_mov_b64 exec, s[0:1]
	s_cbranch_execz .Lxb4_done
	v_mov_b32_e32 v0, 0x22400
	ds_read2_b32 v[0:1], v0 offset1:1
	s_getreg_b32 s6, hwreg(HW_REG_XCC_ID, 0, 4)
	s_and_b32 s6, s6, 15
	s_lshl_b32 s6, s6, 8
	s_addk_i32 s6, 0x1400
	v_mov_b32_e32 v2, s6
	v_mov_b32_e32 v3, 1
	global_atomic_add v2, v2, v3, s[40:41] sc0
	s_waitcnt vmcnt(0) lgkmcnt(0)
	v_readfirstlane_b32 s7, v2
	v_readfirstlane_b32 s8, v0
	v_readfirstlane_b32 s9, v1
	s_mul_i32 s10, s8, 5
	s_add_i32 s7, s7, 1
	s_cmp_lg_u32 s7, s10
	s_cbranch_scc1 .Lxb4_poll
	buffer_wbl2 sc1
	s_waitcnt vmcnt(0)
	v_mov_b32_e32 v2, 0x3400
	global_atomic_add v2, v3, s[40:41]
.Lxb4_poll:
	s_mul_i32 s10, s9, 5
	v_mov_b32_e32 v2, 0x3400
	s_mov_b32 s11, 0

; __device__ __forceinline__ unsigned xb_ld(unsigned* p)              { return __hip_atomic_load(p, __ATOMIC_RELAXED, __HIP_MEMORY_SCOPE_AGENT); }
; __device__ __forceinline__ unsigned xb_add(unsigned* p, unsigned v) { return __hip_atomic_fetch_add(p, v, __ATOMIC_RELAXED, __HIP_MEMORY_SCOPE_AGENT); }
; #define XB_SPIN(cond, bar) do { unsigned _sp = 0; while (cond) { __builtin_amdgcn_s_sleep(1); \
;     if ((++_sp & 255u) == 0u) { if (xb_ld(&(bar)[XB_TMO])) break; if (_sp > XB_SPIN_CAP) { atomicAdd(&(bar)[XB_TMO], 1u); break; } } } } while (0)
; __device__ __forceinline__ void xcd_barrier(const XcdBarrier& b) {
;     asm volatile("s_waitcnt vmcnt(0)" ::: "memory");
;     __syncthreads();
;     if (threadIdx.x == 0) {
;         unsigned* bar = b.bar;
;         __builtin_amdgcn_s_waitcnt(0);
;         unsigned nloc = b.st[0], nx = b.st[1];
;         if (nloc == 0u) { xcd_barrier_complete(bar, b.x, nloc, nx); b.st[0] = nloc; b.st[1] = nx; }
;         const unsigned old = xb_add(&bar[XB_XSUB(b.x)], 1u);
;         const unsigned gen = old / nloc;
;         if (old + 1u == (gen + 1u) * nloc) {
;             __builtin_amdgcn_fence(__ATOMIC_RELEASE, "agent");
;             asm volatile("s_waitcnt vmcnt(0)" ::: "memory");
;             const unsigned og = xb_add(&bar[XB_TOP], 1u);
;             const unsigned tg = og / nx;
;             if (og + 1u == (tg + 1u) * nx) xb_add(&bar[XB_TOPGEN], 1u);
;             else XB_SPIN(xb_ld(&bar[XB_TOPGEN]) == tg, bar);
;             __builtin_amdgcn_fence(__ATOMIC_ACQUIRE, "agent");
;             xb_add(&bar[XB_XGEN(b.x)], 1u);
;             asm volatile("s_waitcnt vmcnt(0)" ::: "memory");
;         } else {
;             XB_SPIN(xb_ld(&bar[XB_XGEN(b.x)]) == gen, bar);
;             __builtin_amdgcn_fence(__ATOMIC_ACQUIRE, "agent");
;             asm volatile("s_waitcnt vmcnt(0)" ::: "memory");
;         }
.LBB0_420:
	s_waitcnt vmcnt(0)
	s_barrier
	s_mov_b64 s[4:5], exec
	v_readlane_b32 s0, v244, 4
	v_readlane_b32 s1, v244, 5
	s_and_b64 s[0:1], s[4:5], s[0:1]
	s_mov_b64 exec, s[0:1]
	s_cbranch_execz .Lxb5_done
	v_mov_b32_e32 v0, 0x22400
	ds_read2_b32 v[0:1], v0 offset1:1
	s_getreg_b32 s6, hwreg(HW_REG_XCC_ID, 0, 4)
	s_and_b32 s6, s6, 15
	s_lshl_b32 s6, s6, 8
	s_addk_i32 s6, 0x1400
	v_mov_b32_e32 v2, s6
	v_mov_b32_e32 v3, 1
	global_atomic_add v2, v2, v3, s[40:41] sc0
	s_waitcnt vmcnt(0) lgkmcnt(0)
	v_readfirstlane_b32 s7, v2
	v_readfirstlane_b32 s8, v0
	v_readfirstlane_b32 s9, v1
	s_mul_i32 s10, s8, 6
	s_add_i32 s7, s7, 1
	s_cmp_lg_u32 s7, s10
	s_cbranch_scc1 .Lxb5_poll
	buffer_wbl2 sc1
	s_waitcnt vmcnt(0)
	v_mov_b32_e32 v2, 0x3400
	global_atomic_add v2, v3, s[40:41]
.Lxb5_poll:
	s_mul_i32 s10, s9, 6
	v_mov_b32_e32 v2, 0x3400
	s_mov_b32 s11, 0

; __device__ __forceinline__ unsigned xb_ld(unsigned* p)              { return __hip_atomic_load(p, __ATOMIC_RELAXED, __HIP_MEMORY_SCOPE_AGENT); }
; __device__ __forceinline__ unsigned xb_add(unsigned* p, unsigned v) { return __hip_atomic_fetch_add(p, v, __ATOMIC_RELAXED, __HIP_MEMORY_SCOPE_AGENT); }
; #define XB_SPIN(cond, bar) do { unsigned _sp = 0; while (cond) { __builtin_amdgcn_s_sleep(1); \
;     if ((++_sp & 255u) == 0u) { if (xb_ld(&(bar)[XB_TMO])) break; if (_sp > XB_SPIN_CAP) { atomicAdd(&(bar)[XB_TMO], 1u); break; } } } } while (0)
; __device__ __forceinline__ void xcd_barrier(const XcdBarrier& b) {
;     asm volatile("s_waitcnt vmcnt(0)" ::: "memory");
;     __syncthreads();
;     if (threadIdx.x == 0) {
;         unsigned* bar = b.bar;
;         __builtin_amdgcn_s_waitcnt(0);
;         unsigned nloc = b.st[0], nx = b.st[1];
;         if (nloc == 0u) { xcd_barrier_complete(bar, b.x, nloc, nx); b.st[0] = nloc; b.st[1] = nx; }
;         const unsigned old = xb_add(&bar[XB_XSUB(b.x)], 1u);
;         const unsigned gen = old / nloc;
;         if (old + 1u == (gen + 1u) * nloc) {
;             __builtin_amdgcn_fence(__ATOMIC_RELEASE, "agent");
;             asm volatile("s_waitcnt vmcnt(0)" ::: "memory");
;             const unsigned og = xb_add(&bar[XB_TOP], 1u);
;             const unsigned tg = og / nx;
;             if (og + 1u == (tg + 1u) * nx) xb_add(&bar[XB_TOPGEN], 1u);
;             else XB_SPIN(xb_ld(&bar[XB_TOPGEN]) == tg, bar);
;             __builtin_amdgcn_fence(__ATOMIC_ACQUIRE, "agent");
;             xb_add(&bar[XB_XGEN(b.x)], 1u);
;             asm volatile("s_waitcnt vmcnt(0)" ::: "memory");
;         } else {
;             XB_SPIN(xb_ld(&bar[XB_XGEN(b.x)]) == gen, bar);
;             __builtin_amdgcn_fence(__ATOMIC_ACQUIRE, "agent");
;             asm volatile("s_waitcnt vmcnt(0)" ::: "memory");
;         }
.LBB0_481:
	s_or_b64 exec, exec, s[6:7]
	s_waitcnt vmcnt(0)
	s_barrier
	s_mov_b64 s[4:5], exec
	v_readlane_b32 s0, v244, 4
	v_readlane_b32 s1, v244, 5
	s_and_b64 s[0:1], s[4:5], s[0:1]
	s_mov_b64 exec, s[0:1]
	s_cbranch_execz .Lxb6_done
	v_mov_b32_e32 v0, 0x22400
	ds_read2_b32 v[0:1], v0 offset1:1
	s_getreg_b32 s6, hwreg(HW_REG_XCC_ID, 0, 4)
	s_and_b32 s6, s6, 15
	s_lshl_b32 s6, s6, 8
	s_addk_i32 s6, 0x1400
	v_mov_b32_e32 v2, s6
	v_mov_b32_e32 v3, 1
	global_atomic_add v2, v2, v3, s[40:41] sc0
	s_waitcnt vmcnt(0) lgkmcnt(0)
	v_readfirstlane_b32 s7, v2
	v_readfirstlane_b32 s8, v0
	v_readfirstlane_b32 s9, v1
	s_mul_i32 s10, s8, 7
	s_add_i32 s7, s7, 1
	s_cmp_lg_u32 s7, s10
	s_cbranch_scc1 .Lxb6_poll
	buffer_wbl2 sc1
	s_waitcnt vmcnt(0)
	v_mov_b32_e32 v2, 0x3400
	global_atomic_add v2, v3, s[40:41]
.Lxb6_poll:
	s_mul_i32 s10, s9, 7
	v_mov_b32_e32 v2, 0x3400
	s_mov_b32 s11, 0

; __device__ __forceinline__ unsigned xb_ld(unsigned* p)              { return __hip_atomic_load(p, __ATOMIC_RELAXED, __HIP_MEMORY_SCOPE_AGENT); }
; __device__ __forceinline__ unsigned xb_add(unsigned* p, unsigned v) { return __hip_atomic_fetch_add(p, v, __ATOMIC_RELAXED, __HIP_MEMORY_SCOPE_AGENT); }
; #define XB_SPIN(cond, bar) do { unsigned _sp = 0; while (cond) { __builtin_amdgcn_s_sleep(1); \
;     if ((++_sp & 255u) == 0u) { if (xb_ld(&(bar)[XB_TMO])) break; if (_sp > XB_SPIN_CAP) { atomicAdd(&(bar)[XB_TMO], 1u); break; } } } } while (0)
; __device__ __forceinline__ void xcd_barrier(const XcdBarrier& b) {
;     asm volatile("s_waitcnt vmcnt(0)" ::: "memory");
;     __syncthreads();
;     if (threadIdx.x == 0) {
;         unsigned* bar = b.bar;
;         __builtin_amdgcn_s_waitcnt(0);
;         unsigned nloc = b.st[0], nx = b.st[1];
;         if (nloc == 0u) { xcd_barrier_complete(bar, b.x, nloc, nx); b.st[0] = nloc; b.st[1] = nx; }
;         const unsigned old = xb_add(&bar[XB_XSUB(b.x)], 1u);
;         const unsigned gen = old / nloc;
;         if (old + 1u == (gen + 1u) * nloc) {
;             __builtin_amdgcn_fence(__ATOMIC_RELEASE, "agent");
;             asm volatile("s_waitcnt vmcnt(0)" ::: "memory");
;             const unsigned og = xb_add(&bar[XB_TOP], 1u);
;             const unsigned tg = og / nx;
;             if (og + 1u == (tg + 1u) * nx) xb_add(&bar[XB_TOPGEN], 1u);
;             else XB_SPIN(xb_ld(&bar[XB_TOPGEN]) == tg, bar);
;             __builtin_amdgcn_fence(__ATOMIC_ACQUIRE, "agent");
;             xb_add(&bar[XB_XGEN(b.x)], 1u);
;             asm volatile("s_waitcnt vmcnt(0)" ::: "memory");
;         } else {
;             XB_SPIN(xb_ld(&bar[XB_XGEN(b.x)]) == gen, bar);
;             __builtin_amdgcn_fence(__ATOMIC_ACQUIRE, "agent");
;             asm volatile("s_waitcnt vmcnt(0)" ::: "memory");
;         }
.LBB0_557:
	s_waitcnt vmcnt(0)
	s_waitcnt vmcnt(0)
	s_barrier
	s_mov_b64 s[2:3], exec
	v_readlane_b32 s0, v244, 4
	v_readlane_b32 s1, v244, 5
	s_and_b64 s[0:1], s[2:3], s[0:1]
	s_mov_b64 exec, s[0:1]
	s_cbranch_execz .Lxb7_done
	v_mov_b32_e32 v0, 0x22400
	ds_read2_b32 v[0:1], v0 offset1:1
	s_getreg_b32 s6, hwreg(HW_REG_XCC_ID, 0, 4)
	s_and_b32 s6, s6, 15
	s_lshl_b32 s6, s6, 8
	s_addk_i32 s6, 0x1400
	v_mov_b32_e32 v2, s6
	v_mov_b32_e32 v3, 1
	global_atomic_add v2, v2, v3, s[40:41] sc0
	s_waitcnt vmcnt(0) lgkmcnt(0)
	v_readfirstlane_b32 s7, v2
	v_readfirstlane_b32 s8, v0
	v_readfirstlane_b32 s9, v1
	s_mul_i32 s10, s8, 8
	s_add_i32 s7, s7, 1
	s_cmp_lg_u32 s7, s10
	s_cbranch_scc1 .Lxb7_poll
	buffer_wbl2 sc1
	s_waitcnt vmcnt(0)
	v_mov_b32_e32 v2, 0x3400
	global_atomic_add v2, v3, s[40:41]
.Lxb7_poll:
	s_mul_i32 s10, s9, 8
	v_mov_b32_e32 v2, 0x3400
	s_mov_b32 s11, 0
